# attention tile loop edges: back edge falls straight into the unmasked body (2 fewer taken branches), It-B mask block moved out of line, DMA address SALU hoisted above the barrier
# baseline (speedup 1.0000x reference)
.Lattn1_mask:
	v_add_u32_e32 v102, 0x60, v238
	v_add_u32_e32 v101, 64, v238
	v_cmp_le_u32_e32 vcc, v102, v236
	s_mov_b64 s[0:1], 0
	s_nop 0
	v_cndmask_b32_e32 v128, v226, v80, vcc
	v_cmp_lt_u32_e32 vcc, v101, v236
	s_nop 1
	v_cndmask_b32_e32 v145, v226, v65, vcc
	v_cmp_le_u32_e32 vcc, v101, v236
	v_add_u32_e32 v101, 0x61, v238
	s_nop 0
	v_cndmask_b32_e32 v144, v226, v64, vcc
	v_cmp_le_u32_e32 vcc, v101, v236
	v_add_u32_e32 v101, 0x42, v238
	s_nop 0
	v_cndmask_b32_e32 v129, v226, v81, vcc
	v_cmp_le_u32_e32 vcc, v101, v236
	v_add_u32_e32 v101, 0x62, v238
	s_nop 0
	v_cndmask_b32_e32 v146, v226, v66, vcc
	v_cmp_le_u32_e32 vcc, v101, v236
	v_add_u32_e32 v101, 0x43, v238
	s_nop 0
	v_cndmask_b32_e32 v130, v226, v82, vcc
	v_cmp_le_u32_e32 vcc, v101, v236
	v_add_u32_e32 v101, 0x63, v238
	s_nop 0
	v_cndmask_b32_e32 v147, v226, v67, vcc
	v_cmp_le_u32_e32 vcc, v101, v236
	v_add_u32_e32 v101, 0x48, v238
	s_nop 0
	v_cndmask_b32_e32 v131, v226, v83, vcc
	v_cmp_le_u32_e32 vcc, v101, v236
	v_add_u32_e32 v101, 0x68, v238
	s_nop 0
	v_cndmask_b32_e32 v148, v226, v68, vcc
	v_cmp_le_u32_e32 vcc, v101, v236
	v_add_u32_e32 v101, 0x49, v238
	s_nop 0
	v_cndmask_b32_e32 v132, v226, v84, vcc
	v_cmp_le_u32_e32 vcc, v101, v236
	v_add_u32_e32 v101, 0x69, v238
	s_nop 0
	v_cndmask_b32_e32 v149, v226, v69, vcc
	v_cmp_le_u32_e32 vcc, v101, v236
	v_add_u32_e32 v101, 0x4a, v238
	s_nop 0
	v_cndmask_b32_e32 v133, v226, v85, vcc
	v_cmp_le_u32_e32 vcc, v101, v236
	v_add_u32_e32 v101, 0x6a, v238
	s_nop 0
	v_cndmask_b32_e32 v150, v226, v70, vcc
	v_cmp_le_u32_e32 vcc, v101, v236
	v_add_u32_e32 v101, 0x4b, v238
	s_nop 0
	v_cndmask_b32_e32 v134, v226, v86, vcc
	v_cmp_le_u32_e32 vcc, v101, v236
	v_add_u32_e32 v101, 0x6b, v238
	s_nop 0
	v_cndmask_b32_e32 v151, v226, v71, vcc
	v_cmp_le_u32_e32 vcc, v101, v236
	v_add_u32_e32 v101, 0x50, v238
	s_nop 0
	v_cndmask_b32_e32 v135, v226, v87, vcc
	v_cmp_le_u32_e32 vcc, v101, v236
	v_add_u32_e32 v101, 0x70, v238
	s_nop 0
	v_cndmask_b32_e32 v152, v226, v72, vcc
	v_cmp_le_u32_e32 vcc, v101, v236
	v_add_u32_e32 v101, 0x51, v238
	s_nop 0
	v_cndmask_b32_e32 v136, v226, v88, vcc
	v_cmp_le_u32_e32 vcc, v101, v236
	v_add_u32_e32 v101, 0x71, v238
	s_nop 0
	v_cndmask_b32_e32 v153, v226, v73, vcc
	v_cmp_le_u32_e32 vcc, v101, v236
	v_add_u32_e32 v101, 0x52, v238
	s_nop 0
	v_cndmask_b32_e32 v137, v226, v89, vcc
	v_cmp_le_u32_e32 vcc, v101, v236
	v_add_u32_e32 v101, 0x72, v238
	s_nop 0
	v_cndmask_b32_e32 v154, v226, v74, vcc
	v_cmp_le_u32_e32 vcc, v101, v236
	v_add_u32_e32 v101, 0x53, v238
	s_nop 0
	v_cndmask_b32_e32 v138, v226, v90, vcc
	v_cmp_le_u32_e32 vcc, v101, v236
	v_add_u32_e32 v101, 0x73, v238
	s_nop 0
	v_cndmask_b32_e32 v155, v226, v75, vcc
	v_cmp_le_u32_e32 vcc, v101, v236
	v_add_u32_e32 v101, 0x58, v238
	s_nop 0
	v_cndmask_b32_e32 v139, v226, v91, vcc
	v_cmp_le_u32_e32 vcc, v101, v236
	v_add_u32_e32 v101, 0x78, v238
	s_nop 0
	v_cndmask_b32_e32 v156, v226, v76, vcc
	v_cmp_le_u32_e32 vcc, v101, v236
	v_add_u32_e32 v101, 0x59, v238
	s_nop 0
	v_cndmask_b32_e32 v140, v226, v92, vcc
	v_cmp_le_u32_e32 vcc, v101, v236
	v_add_u32_e32 v101, 0x79, v238
	s_nop 0
	v_cndmask_b32_e32 v157, v226, v77, vcc
	v_cmp_le_u32_e32 vcc, v101, v236
	v_add_u32_e32 v101, 0x5a, v238
	s_nop 0
	v_cndmask_b32_e32 v141, v226, v93, vcc
	v_cmp_le_u32_e32 vcc, v101, v236
	v_add_u32_e32 v101, 0x7a, v238
	s_nop 0
	v_cndmask_b32_e32 v158, v226, v78, vcc
	v_cmp_le_u32_e32 vcc, v101, v236
	v_add_u32_e32 v101, 0x5b, v238
	s_nop 0
	v_cndmask_b32_e32 v142, v226, v94, vcc
	v_cmp_le_u32_e32 vcc, v101, v236
	v_add_u32_e32 v101, 0x7b, v238
	s_nop 0
	v_cndmask_b32_e32 v159, v226, v79, vcc
	v_cmp_le_u32_e32 vcc, v101, v236
	s_nop 1
	v_cndmask_b32_e32 v143, v226, v95, vcc

.Lattn1_nomask:
	s_add_i32 s9, s78, 0x10000
	s_and_b32 s33, s9, 0x18000
	s_and_b32 s76, s78, 0x18000
	v_add_u32_e32 v250, s33, v237
	v_add_u32_e32 v250, v250, v228
	ds_read_b128 v[128:131], v250 offset:16384
	ds_read_b128 v[132:135], v250 offset:20480
	ds_read_b128 v[136:139], v250 offset:24576
	ds_read_b128 v[140:143], v250 offset:28672
	v_add_u32_e32 v251, s76, v235
	v_add_u32_e32 v250, v251, v228
	ds_read_b128 v[144:147], v250
	ds_read_b128 v[148:151], v250 offset:4096
	v_add_u32_e32 v250, v251, v231
	ds_read_b128 v[152:155], v250
	ds_read_b128 v[156:159], v250 offset:4096
	s_add_i32 s0, s74, s38
	s_addk_i32 s0, 0xc0
	s_mul_i32 s0, s0, s14
	s_lshl_b32 s92, s46, 1
	s_add_i32 s0, s0, s92
	s_addk_i32 s0, 0x1c00
	s_add_u32 s98, s82, s0
	s_addc_u32 s99, s83, 0
	s_add_i32 s0, s78, 0x8000
	s_and_b32 s0, s0, 0x18000
	s_add_i32 s0, s5, s0
	s_mov_b32 m0, s0
	s_nop 0
	global_load_lds_dwordx4 v244, s[98:99]
	s_add_i32 m0, s0, 0x2000
	s_add_u32 s98, s98, 0x80
	s_addc_u32 s99, s99, 0
	global_load_lds_dwordx4 v244, s[98:99]
	s_lshl_b32 s1, s17, 13
	s_add_u32 s98, s40, s1
	s_addc_u32 s99, s41, 0
	s_add_i32 m0, s0, 0x4000
	s_nop 0
	global_load_lds_dwordx4 v245, s[98:99]
	s_add_i32 m0, s0, 0x6000
	s_add_u32 s98, s98, 0x80000
	s_addc_u32 s99, s99, 0
	global_load_lds_dwordx4 v245, s[98:99]
	v_max3_f32 v246, v64, v65, v66
	v_max3_f32 v247, v72, v73, v74
	v_max3_f32 v248, v80, v81, v82
	v_max3_f32 v249, v88, v89, v90
	v_max3_f32 v246, v246, v67, v68
	v_max3_f32 v247, v247, v75, v76
	v_max3_f32 v248, v248, v83, v84
	v_max3_f32 v249, v249, v91, v92
	s_waitcnt lgkmcnt(7)
	v_mfma_f32_32x32x16_bf16 v[0:15], v[128:131], v[96:99], v[0:15]
	v_max3_f32 v246, v246, v69, v70
	v_max3_f32 v247, v247, v77, v78
	v_max3_f32 v248, v248, v85, v86
	v_max3_f32 v249, v249, v93, v94
	v_max3_f32 v246, v246, v71, v247
	v_max3_f32 v247, v248, v87, v249
	v_max_f32_e32 v248, v212, v212
	s_waitcnt lgkmcnt(6)
	v_mfma_f32_32x32x16_bf16 v[48:63], v[132:135], v[96:99], v[48:63]
	v_max3_f32 v246, v246, v79, v95
	s_nop 0
	v_max3_f32 v246, v246, v247, v247
	s_nop 0
	v_mov_b32_e32 v247, v246
	s_nop 1
	v_permlane32_swap_b32_e32 v246, v247
	v_max3_f32 v246, v246, v247, v247
	s_nop 0
	v_max_f32_e32 v247, v246, v246
	v_max_f32_e32 v251, v248, v247
	s_waitcnt lgkmcnt(5)
	v_mfma_f32_32x32x16_bf16 v[32:47], v[136:139], v[96:99], v[32:47]
	v_sub_f32_e32 v247, v212, v251
	v_exp_f32_e32 v250, v247
	v_add_f32_e32 v247, 0x41000000, v212
	v_cmp_gt_f32_e32 vcc, v246, v247
	s_cmp_eq_u64 vcc, 0
	v_mul_f32_e32 v246, v100, v250
	s_cselect_b64 s[0:1], -1, 0
	v_cndmask_b32_e64 v194, v246, v100, s[0:1]
	s_waitcnt lgkmcnt(4)
	v_mfma_f32_32x32x16_bf16 v[16:31], v[140:143], v[96:99], v[16:31]
	v_cndmask_b32_e64 v212, v251, v212, s[0:1]
	v_mov_b32_e32 v213, v212
	v_sub_f32_e32 v140, v92, v212
	v_sub_f32_e32 v141, v93, v213
	v_sub_f32_e32 v138, v90, v212
	v_sub_f32_e32 v139, v91, v213
	s_waitcnt lgkmcnt(3)
	v_mfma_f32_32x32x16_bf16 v[96:111], v[144:147], v[160:163], 0
	v_sub_f32_e32 v142, v94, v212
	v_sub_f32_e32 v143, v95, v213
	v_sub_f32_e32 v92, v80, v212
	v_sub_f32_e32 v93, v81, v213
	v_sub_f32_e32 v128, v82, v212
	v_sub_f32_e32 v129, v83, v213
	s_waitcnt lgkmcnt(2)
	v_mfma_f32_32x32x16_bf16 v[112:127], v[148:151], v[160:163], 0
	v_sub_f32_e32 v130, v68, v212
	v_sub_f32_e32 v131, v69, v213
	v_sub_f32_e32 v90, v64, v212
	v_sub_f32_e32 v91, v65, v213
	v_sub_f32_e32 v132, v84, v212
	v_sub_f32_e32 v133, v85, v213
	s_waitcnt lgkmcnt(1)
	v_mfma_f32_32x32x16_bf16 v[96:111], v[152:155], v[164:167], v[96:111]
	v_sub_f32_e32 v94, v66, v212
	v_sub_f32_e32 v95, v67, v213
	v_sub_f32_e32 v134, v86, v212
	v_sub_f32_e32 v135, v87, v213
	v_sub_f32_e32 v136, v88, v212
	v_sub_f32_e32 v137, v89, v213
	s_waitcnt lgkmcnt(0)
	v_mfma_f32_32x32x16_bf16 v[112:127], v[156:159], v[164:167], v[112:127]
	v_sub_f32_e32 v144, v70, v212
	v_sub_f32_e32 v145, v71, v213
	v_sub_f32_e32 v148, v74, v212
	v_sub_f32_e32 v149, v75, v213
	v_sub_f32_e32 v150, v76, v212
	v_sub_f32_e32 v151, v77, v213
	v_sub_f32_e32 v146, v72, v212
	v_sub_f32_e32 v147, v73, v213
	v_sub_f32_e32 v152, v78, v212
	v_sub_f32_e32 v153, v79, v213
	v_mov_b32_e32 v68, v250
	s_branch .Lattn_body_1

.LBB0_836:
	s_add_i32 s79, s10, 2
	s_cmp_ge_u32 s79, s8
	s_cselect_b64 s[76:77], -1, 0
	s_and_b64 vcc, exec, s[76:77]
	s_add_i32 s0, s74, s38
	s_addk_i32 s0, 0x100
	s_mul_i32 s0, s0, s14
	s_lshl_b32 s92, s46, 1
	s_add_i32 s0, s0, s92
	s_addk_i32 s0, 0x1c00
	s_add_u32 s98, s82, s0
	s_addc_u32 s99, s83, 0
	s_lshl_b32 s1, s17, 13
	s_add_u32 s0, s40, s1
	s_addc_u32 s1, s41, 0
	s_add_u32 s0, s0, 0x80
	s_addc_u32 s1, s1, 0
	s_add_i32 s32, s5, s33
	s_waitcnt vmcnt(2)
	s_barrier
	s_cbranch_vccnz .LBB0_838
	s_mov_b32 m0, s32
	s_nop 0
	global_load_lds_dwordx4 v244, s[98:99]
	s_add_i32 m0, s32, 0x2000
	s_add_u32 s98, s98, 0x80
	s_addc_u32 s99, s99, 0
	global_load_lds_dwordx4 v244, s[98:99]
	s_add_i32 m0, s32, 0x4000
	s_nop 0
	global_load_lds_dwordx4 v245, s[0:1]
	s_add_i32 m0, s32, 0x6000
	s_add_u32 s0, s0, 0x80000
	s_addc_u32 s1, s1, 0
	global_load_lds_dwordx4 v245, s[0:1]
.LBB0_838:
	s_cmp_lt_u32 s10, s35
	s_cbranch_scc0 .Lattn1_maskB

.LBB0_842:
	s_add_u32 s38, s38, 0x80
	s_addc_u32 s39, s39, 0
	s_add_u32 s40, s40, 0x100
	s_addc_u32 s41, s41, 0
	s_and_b64 vcc, exec, s[76:77]
	s_waitcnt vmcnt(2)
	s_barrier
	s_cbranch_vccnz .LBB0_844
	s_mov_b32 s78, s9
	s_mov_b32 s10, s79
	s_add_i32 s9, s10, -1
	s_mov_b64 s[0:1], -1
	s_cmp_ge_u32 s9, s35
	v_add_u32_e32 v238, s38, v208
	s_cbranch_scc1 .Lattn1_mask
	s_branch .Lattn1_nomask
.Lattn1_maskB:
	v_add_u32_e32 v70, 0xa0, v238
	v_add_u32_e32 v68, 0x80, v238
	v_cmp_le_u32_e32 vcc, v70, v236
	s_nop 1
	v_cndmask_b32_e32 v112, v226, v112, vcc
	v_cmp_lt_u32_e32 vcc, v68, v236
	s_nop 1
	v_cndmask_b32_e32 v97, v226, v97, vcc
	v_cmp_le_u32_e32 vcc, v68, v236
	v_add_u32_e32 v68, 0xa1, v238
	s_nop 0
	v_cndmask_b32_e32 v96, v226, v96, vcc
	v_cmp_le_u32_e32 vcc, v68, v236
	v_add_u32_e32 v68, 0x82, v238
	s_nop 0
	v_cndmask_b32_e32 v113, v226, v113, vcc
	v_cmp_le_u32_e32 vcc, v68, v236
	v_add_u32_e32 v68, 0xa2, v238
	s_nop 0
	v_cndmask_b32_e32 v98, v226, v98, vcc
	v_cmp_le_u32_e32 vcc, v68, v236
	v_add_u32_e32 v68, 0x83, v238
	s_nop 0
	v_cndmask_b32_e32 v114, v226, v114, vcc
	v_cmp_le_u32_e32 vcc, v68, v236
	v_add_u32_e32 v68, 0xa3, v238
	s_nop 0
	v_cndmask_b32_e32 v99, v226, v99, vcc
	v_cmp_le_u32_e32 vcc, v68, v236
	v_add_u32_e32 v68, 0x88, v238
	s_nop 0
	v_cndmask_b32_e32 v115, v226, v115, vcc
	v_cmp_le_u32_e32 vcc, v68, v236
	v_add_u32_e32 v68, 0xa8, v238
	s_nop 0
	v_cndmask_b32_e32 v100, v226, v100, vcc
	v_cmp_le_u32_e32 vcc, v68, v236
	v_add_u32_e32 v68, 0x89, v238
	s_nop 0
	v_cndmask_b32_e32 v116, v226, v116, vcc
	v_cmp_le_u32_e32 vcc, v68, v236
	v_add_u32_e32 v68, 0xa9, v238
	s_nop 0
	v_cndmask_b32_e32 v101, v226, v101, vcc
	v_cmp_le_u32_e32 vcc, v68, v236
	v_add_u32_e32 v68, 0x8a, v238
	s_nop 0
	v_cndmask_b32_e32 v117, v226, v117, vcc
	v_cmp_le_u32_e32 vcc, v68, v236
	v_add_u32_e32 v68, 0xaa, v238
	s_nop 0
	v_cndmask_b32_e32 v102, v226, v102, vcc
	v_cmp_le_u32_e32 vcc, v68, v236
	v_add_u32_e32 v68, 0x8b, v238
	s_nop 0
	v_cndmask_b32_e32 v118, v226, v118, vcc
	v_cmp_le_u32_e32 vcc, v68, v236
	v_add_u32_e32 v68, 0xab, v238
	s_nop 0
	v_cndmask_b32_e32 v103, v226, v103, vcc
	v_cmp_le_u32_e32 vcc, v68, v236
	v_add_u32_e32 v68, 0x90, v238
	s_nop 0
	v_cndmask_b32_e32 v119, v226, v119, vcc
	v_cmp_le_u32_e32 vcc, v68, v236
	v_add_u32_e32 v68, 0xb0, v238
	s_nop 0
	v_cndmask_b32_e32 v104, v226, v104, vcc
	v_cmp_le_u32_e32 vcc, v68, v236
	v_add_u32_e32 v68, 0x91, v238
	s_nop 0
	v_cndmask_b32_e32 v120, v226, v120, vcc
	v_cmp_le_u32_e32 vcc, v68, v236
	v_add_u32_e32 v68, 0xb1, v238
	s_nop 0
	v_cndmask_b32_e32 v105, v226, v105, vcc
	v_cmp_le_u32_e32 vcc, v68, v236
	v_add_u32_e32 v68, 0x92, v238
	s_nop 0
	v_cndmask_b32_e32 v121, v226, v121, vcc
	v_cmp_le_u32_e32 vcc, v68, v236
	v_add_u32_e32 v68, 0xb2, v238
	s_nop 0
	v_cndmask_b32_e32 v106, v226, v106, vcc
	v_cmp_le_u32_e32 vcc, v68, v236
	v_add_u32_e32 v68, 0x93, v238
	s_nop 0
	v_cndmask_b32_e32 v122, v226, v122, vcc
	v_cmp_le_u32_e32 vcc, v68, v236
	v_add_u32_e32 v68, 0xb3, v238
	s_nop 0
	v_cndmask_b32_e32 v107, v226, v107, vcc
	v_cmp_le_u32_e32 vcc, v68, v236
	v_add_u32_e32 v68, 0x98, v238
	s_nop 0
	v_cndmask_b32_e32 v123, v226, v123, vcc
	v_cmp_le_u32_e32 vcc, v68, v236
	v_add_u32_e32 v68, 0xb8, v238
	s_nop 0
	v_cndmask_b32_e32 v108, v226, v108, vcc
	v_cmp_le_u32_e32 vcc, v68, v236
	v_add_u32_e32 v68, 0x99, v238
	s_nop 0
	v_cndmask_b32_e32 v124, v226, v124, vcc
	v_cmp_le_u32_e32 vcc, v68, v236
	v_add_u32_e32 v68, 0xb9, v238
	s_nop 0
	v_cndmask_b32_e32 v109, v226, v109, vcc
	v_cmp_le_u32_e32 vcc, v68, v236
	v_add_u32_e32 v68, 0x9a, v238
	s_nop 0
	v_cndmask_b32_e32 v125, v226, v125, vcc
	v_cmp_le_u32_e32 vcc, v68, v236
	v_add_u32_e32 v68, 0xba, v238
	s_nop 0
	v_cndmask_b32_e32 v110, v226, v110, vcc
	v_cmp_le_u32_e32 vcc, v68, v236
	v_add_u32_e32 v68, 0x9b, v238
	s_nop 0
	v_cndmask_b32_e32 v126, v226, v126, vcc
	v_cmp_le_u32_e32 vcc, v68, v236
	v_add_u32_e32 v68, 0xbb, v238
	s_nop 0
	v_cndmask_b32_e32 v111, v226, v111, vcc
	v_cmp_le_u32_e32 vcc, v68, v236
	s_nop 1
	v_cndmask_b32_e32 v127, v226, v127, vcc
	s_branch .LBB0_840

.Lattn2_mask:
	v_add_u32_e32 v102, 0x60, v238
	v_add_u32_e32 v101, 64, v238
	v_cmp_le_u32_e32 vcc, v102, v235
	s_mov_b64 s[0:1], 0
	s_nop 0
	v_cndmask_b32_e32 v128, v226, v80, vcc
	v_cmp_lt_u32_e32 vcc, v101, v235
	s_nop 1
	v_cndmask_b32_e32 v145, v226, v65, vcc
	v_cmp_le_u32_e32 vcc, v101, v235
	v_add_u32_e32 v101, 0x61, v238
	s_nop 0
	v_cndmask_b32_e32 v144, v226, v64, vcc
	v_cmp_le_u32_e32 vcc, v101, v235
	v_add_u32_e32 v101, 0x42, v238
	s_nop 0
	v_cndmask_b32_e32 v129, v226, v81, vcc
	v_cmp_le_u32_e32 vcc, v101, v235
	v_add_u32_e32 v101, 0x62, v238
	s_nop 0
	v_cndmask_b32_e32 v146, v226, v66, vcc
	v_cmp_le_u32_e32 vcc, v101, v235
	v_add_u32_e32 v101, 0x43, v238
	s_nop 0
	v_cndmask_b32_e32 v130, v226, v82, vcc
	v_cmp_le_u32_e32 vcc, v101, v235
	v_add_u32_e32 v101, 0x63, v238
	s_nop 0
	v_cndmask_b32_e32 v147, v226, v67, vcc
	v_cmp_le_u32_e32 vcc, v101, v235
	v_add_u32_e32 v101, 0x48, v238
	s_nop 0
	v_cndmask_b32_e32 v131, v226, v83, vcc
	v_cmp_le_u32_e32 vcc, v101, v235
	v_add_u32_e32 v101, 0x68, v238
	s_nop 0
	v_cndmask_b32_e32 v148, v226, v68, vcc
	v_cmp_le_u32_e32 vcc, v101, v235
	v_add_u32_e32 v101, 0x49, v238
	s_nop 0
	v_cndmask_b32_e32 v132, v226, v84, vcc
	v_cmp_le_u32_e32 vcc, v101, v235
	v_add_u32_e32 v101, 0x69, v238
	s_nop 0
	v_cndmask_b32_e32 v149, v226, v69, vcc
	v_cmp_le_u32_e32 vcc, v101, v235
	v_add_u32_e32 v101, 0x4a, v238
	s_nop 0
	v_cndmask_b32_e32 v133, v226, v85, vcc
	v_cmp_le_u32_e32 vcc, v101, v235
	v_add_u32_e32 v101, 0x6a, v238
	s_nop 0
	v_cndmask_b32_e32 v150, v226, v70, vcc
	v_cmp_le_u32_e32 vcc, v101, v235
	v_add_u32_e32 v101, 0x4b, v238
	s_nop 0
	v_cndmask_b32_e32 v134, v226, v86, vcc
	v_cmp_le_u32_e32 vcc, v101, v235
	v_add_u32_e32 v101, 0x6b, v238
	s_nop 0
	v_cndmask_b32_e32 v151, v226, v71, vcc
	v_cmp_le_u32_e32 vcc, v101, v235
	v_add_u32_e32 v101, 0x50, v238
	s_nop 0
	v_cndmask_b32_e32 v135, v226, v87, vcc
	v_cmp_le_u32_e32 vcc, v101, v235
	v_add_u32_e32 v101, 0x70, v238
	s_nop 0
	v_cndmask_b32_e32 v152, v226, v72, vcc
	v_cmp_le_u32_e32 vcc, v101, v235
	v_add_u32_e32 v101, 0x51, v238
	s_nop 0
	v_cndmask_b32_e32 v136, v226, v88, vcc
	v_cmp_le_u32_e32 vcc, v101, v235
	v_add_u32_e32 v101, 0x71, v238
	s_nop 0
	v_cndmask_b32_e32 v153, v226, v73, vcc
	v_cmp_le_u32_e32 vcc, v101, v235
	v_add_u32_e32 v101, 0x52, v238
	s_nop 0
	v_cndmask_b32_e32 v137, v226, v89, vcc
	v_cmp_le_u32_e32 vcc, v101, v235
	v_add_u32_e32 v101, 0x72, v238
	s_nop 0
	v_cndmask_b32_e32 v154, v226, v74, vcc
	v_cmp_le_u32_e32 vcc, v101, v235
	v_add_u32_e32 v101, 0x53, v238
	s_nop 0
	v_cndmask_b32_e32 v138, v226, v90, vcc
	v_cmp_le_u32_e32 vcc, v101, v235
	v_add_u32_e32 v101, 0x73, v238
	s_nop 0
	v_cndmask_b32_e32 v155, v226, v75, vcc
	v_cmp_le_u32_e32 vcc, v101, v235
	v_add_u32_e32 v101, 0x58, v238
	s_nop 0
	v_cndmask_b32_e32 v139, v226, v91, vcc
	v_cmp_le_u32_e32 vcc, v101, v235
	v_add_u32_e32 v101, 0x78, v238
	s_nop 0
	v_cndmask_b32_e32 v156, v226, v76, vcc
	v_cmp_le_u32_e32 vcc, v101, v235
	v_add_u32_e32 v101, 0x59, v238
	s_nop 0
	v_cndmask_b32_e32 v140, v226, v92, vcc
	v_cmp_le_u32_e32 vcc, v101, v235
	v_add_u32_e32 v101, 0x79, v238
	s_nop 0
	v_cndmask_b32_e32 v157, v226, v77, vcc
	v_cmp_le_u32_e32 vcc, v101, v235
	v_add_u32_e32 v101, 0x5a, v238
	s_nop 0
	v_cndmask_b32_e32 v141, v226, v93, vcc
	v_cmp_le_u32_e32 vcc, v101, v235
	v_add_u32_e32 v101, 0x7a, v238
	s_nop 0
	v_cndmask_b32_e32 v158, v226, v78, vcc
	v_cmp_le_u32_e32 vcc, v101, v235
	v_add_u32_e32 v101, 0x5b, v238
	s_nop 0
	v_cndmask_b32_e32 v142, v226, v94, vcc
	v_cmp_le_u32_e32 vcc, v101, v235
	v_add_u32_e32 v101, 0x7b, v238
	s_nop 0
	v_cndmask_b32_e32 v159, v226, v79, vcc
	v_cmp_le_u32_e32 vcc, v101, v235
	s_nop 1
	v_cndmask_b32_e32 v143, v226, v95, vcc

.Lattn2_nomask:
	s_add_i32 s9, s34, 0x10000
	s_and_b32 s33, s9, 0x18000
	s_and_b32 s10, s34, 0x18000
	v_add_u32_e32 v250, s33, v237
	v_add_u32_e32 v250, v250, v230
	ds_read_b128 v[128:131], v250 offset:16384
	ds_read_b128 v[132:135], v250 offset:20480
	ds_read_b128 v[136:139], v250 offset:24576
	ds_read_b128 v[140:143], v250 offset:28672
	v_add_u32_e32 v251, s10, v236
	v_add_u32_e32 v250, v251, v230
	ds_read_b128 v[144:147], v250
	ds_read_b128 v[148:151], v250 offset:4096
	v_add_u32_e32 v250, v251, v233
	ds_read_b128 v[152:155], v250
	ds_read_b128 v[156:159], v250 offset:4096
	s_add_i32 s0, s74, s64
	s_addk_i32 s0, 0xc0
	s_mul_i32 s0, s0, s14
	s_add_i32 s0, s0, s92
	s_addk_i32 s0, 0x1c00
	s_add_u32 s98, s82, s0
	s_addc_u32 s99, s83, 0
	s_lshl_b32 s1, s17, 13
	s_add_u32 s46, s76, s1
	s_addc_u32 s47, s77, 0
	s_add_i32 s0, s34, 0x8000
	s_and_b32 s0, s0, 0x18000
	s_add_i32 s0, s5, s0
	s_mov_b32 m0, s0
	s_nop 0
	global_load_lds_dwordx4 v244, s[98:99]
	s_add_i32 m0, s0, 0x2000
	s_add_u32 s98, s98, 0x80
	s_addc_u32 s99, s99, 0
	global_load_lds_dwordx4 v244, s[98:99]
	s_add_i32 m0, s0, 0x4000
	s_nop 0
	global_load_lds_dwordx4 v245, s[46:47]
	s_add_i32 m0, s0, 0x6000
	s_add_u32 s46, s46, 0x80000
	s_addc_u32 s47, s47, 0
	global_load_lds_dwordx4 v245, s[46:47]
	v_max3_f32 v246, v64, v65, v66
	v_max3_f32 v247, v72, v73, v74
	v_max3_f32 v248, v80, v81, v82
	v_max3_f32 v249, v88, v89, v90
	v_max3_f32 v246, v246, v67, v68
	v_max3_f32 v247, v247, v75, v76
	v_max3_f32 v248, v248, v83, v84
	v_max3_f32 v249, v249, v91, v92
	s_waitcnt lgkmcnt(7)
	v_mfma_f32_32x32x16_bf16 v[0:15], v[128:131], v[96:99], v[0:15]
	v_max3_f32 v246, v246, v69, v70
	v_max3_f32 v247, v247, v77, v78
	v_max3_f32 v248, v248, v85, v86
	v_max3_f32 v249, v249, v93, v94
	v_max3_f32 v246, v246, v71, v247
	v_max3_f32 v247, v248, v87, v249
	v_max_f32_e32 v248, v214, v214
	s_waitcnt lgkmcnt(6)
	v_mfma_f32_32x32x16_bf16 v[48:63], v[132:135], v[96:99], v[48:63]
	v_max3_f32 v246, v246, v79, v95
	s_nop 0
	v_max3_f32 v246, v246, v247, v247
	s_nop 0
	v_mov_b32_e32 v247, v246
	s_nop 1
	v_permlane32_swap_b32_e32 v246, v247
	v_max3_f32 v246, v246, v247, v247
	s_nop 0
	v_max_f32_e32 v247, v246, v246
	v_max_f32_e32 v251, v248, v247
	s_waitcnt lgkmcnt(5)
	v_mfma_f32_32x32x16_bf16 v[32:47], v[136:139], v[96:99], v[32:47]
	v_sub_f32_e32 v247, v214, v251
	v_exp_f32_e32 v250, v247
	v_add_f32_e32 v247, 0x41000000, v214
	v_cmp_gt_f32_e32 vcc, v246, v247
	s_cmp_eq_u64 vcc, 0
	v_mul_f32_e32 v246, v100, v250
	s_cselect_b64 s[0:1], -1, 0
	v_cndmask_b32_e64 v194, v246, v100, s[0:1]
	s_waitcnt lgkmcnt(4)
	v_mfma_f32_32x32x16_bf16 v[16:31], v[140:143], v[96:99], v[16:31]
	v_cndmask_b32_e64 v214, v251, v214, s[0:1]
	v_mov_b32_e32 v215, v214
	v_sub_f32_e32 v140, v92, v214
	v_sub_f32_e32 v141, v93, v215
	v_sub_f32_e32 v138, v90, v214
	v_sub_f32_e32 v139, v91, v215
	s_waitcnt lgkmcnt(3)
	v_mfma_f32_32x32x16_bf16 v[96:111], v[144:147], v[160:163], 0
	v_sub_f32_e32 v142, v94, v214
	v_sub_f32_e32 v143, v95, v215
	v_sub_f32_e32 v92, v80, v214
	v_sub_f32_e32 v93, v81, v215
	v_sub_f32_e32 v128, v82, v214
	v_sub_f32_e32 v129, v83, v215
	s_waitcnt lgkmcnt(2)
	v_mfma_f32_32x32x16_bf16 v[112:127], v[148:151], v[160:163], 0
	v_sub_f32_e32 v130, v68, v214
	v_sub_f32_e32 v131, v69, v215
	v_sub_f32_e32 v90, v64, v214
	v_sub_f32_e32 v91, v65, v215
	v_sub_f32_e32 v132, v84, v214
	v_sub_f32_e32 v133, v85, v215
	s_waitcnt lgkmcnt(1)
	v_mfma_f32_32x32x16_bf16 v[96:111], v[152:155], v[164:167], v[96:111]
	v_sub_f32_e32 v94, v66, v214
	v_sub_f32_e32 v95, v67, v215
	v_sub_f32_e32 v134, v86, v214
	v_sub_f32_e32 v135, v87, v215
	v_sub_f32_e32 v136, v88, v214
	v_sub_f32_e32 v137, v89, v215
	s_waitcnt lgkmcnt(0)
	v_mfma_f32_32x32x16_bf16 v[112:127], v[156:159], v[164:167], v[112:127]
	v_sub_f32_e32 v144, v70, v214
	v_sub_f32_e32 v145, v71, v215
	v_sub_f32_e32 v148, v74, v214
	v_sub_f32_e32 v149, v75, v215
	v_sub_f32_e32 v150, v76, v214
	v_sub_f32_e32 v151, v77, v215
	v_sub_f32_e32 v146, v72, v214
	v_sub_f32_e32 v147, v73, v215
	v_sub_f32_e32 v152, v78, v214
	v_sub_f32_e32 v153, v79, v215
	v_mov_b32_e32 v68, v250
	s_branch .Lattn_body_2

.LBB0_866:
	s_add_i32 s10, s35, 2
	s_cmp_ge_u32 s10, s18
	s_cselect_b64 s[90:91], -1, 0
	s_and_b64 vcc, exec, s[90:91]
	s_add_i32 s0, s74, s64
	s_addk_i32 s0, 0x100
	s_mul_i32 s0, s0, s14
	s_add_i32 s0, s0, s92
	s_addk_i32 s0, 0x1c00
	s_add_u32 s98, s82, s0
	s_addc_u32 s99, s83, 0
	s_lshl_b32 s1, s17, 13
	s_add_u32 s0, s76, s1
	s_addc_u32 s1, s77, 0
	s_add_u32 s0, s0, 0x80
	s_addc_u32 s1, s1, 0
	s_add_i32 s32, s5, s33
	s_waitcnt vmcnt(2)
	s_barrier
	s_cbranch_vccnz .LBB0_868
	s_mov_b32 m0, s32
	s_nop 0
	global_load_lds_dwordx4 v244, s[98:99]
	s_add_i32 m0, s32, 0x2000
	s_add_u32 s98, s98, 0x80
	s_addc_u32 s99, s99, 0
	global_load_lds_dwordx4 v244, s[98:99]
	s_add_i32 m0, s32, 0x4000
	s_nop 0
	global_load_lds_dwordx4 v245, s[0:1]
	s_add_i32 m0, s32, 0x6000
	s_add_u32 s0, s0, 0x80000
	s_addc_u32 s1, s1, 0
	global_load_lds_dwordx4 v245, s[0:1]
.LBB0_868:
	s_cmp_lt_u32 s35, s8
	s_cbranch_scc0 .Lattn2_maskB

.LBB0_872:
	s_add_u32 s64, s64, 0x80
	s_addc_u32 s65, s65, 0
	s_add_u32 s76, s76, 0x100
	s_addc_u32 s77, s77, 0
	s_and_b64 vcc, exec, s[90:91]
	s_waitcnt vmcnt(2)
	s_barrier
	s_cbranch_vccnz .LBB0_875
	s_mov_b32 s34, s9
	s_mov_b32 s35, s10
	s_add_i32 s9, s35, -1
	s_mov_b64 s[0:1], -1
	s_cmp_ge_u32 s9, s8
	v_add_u32_e32 v238, s64, v208
	s_cbranch_scc1 .Lattn2_mask
	s_branch .Lattn2_nomask
.Lattn2_maskB:
	v_add_u32_e32 v70, 0xa0, v238
	v_add_u32_e32 v68, 0x80, v238
	v_cmp_le_u32_e32 vcc, v70, v235
	s_nop 1
	v_cndmask_b32_e32 v112, v226, v112, vcc
	v_cmp_lt_u32_e32 vcc, v68, v235
	s_nop 1
	v_cndmask_b32_e32 v97, v226, v97, vcc
	v_cmp_le_u32_e32 vcc, v68, v235
	v_add_u32_e32 v68, 0xa1, v238
	s_nop 0
	v_cndmask_b32_e32 v96, v226, v96, vcc
	v_cmp_le_u32_e32 vcc, v68, v235
	v_add_u32_e32 v68, 0x82, v238
	s_nop 0
	v_cndmask_b32_e32 v113, v226, v113, vcc
	v_cmp_le_u32_e32 vcc, v68, v235
	v_add_u32_e32 v68, 0xa2, v238
	s_nop 0
	v_cndmask_b32_e32 v98, v226, v98, vcc
	v_cmp_le_u32_e32 vcc, v68, v235
	v_add_u32_e32 v68, 0x83, v238
	s_nop 0
	v_cndmask_b32_e32 v114, v226, v114, vcc
	v_cmp_le_u32_e32 vcc, v68, v235
	v_add_u32_e32 v68, 0xa3, v238
	s_nop 0
	v_cndmask_b32_e32 v99, v226, v99, vcc
	v_cmp_le_u32_e32 vcc, v68, v235
	v_add_u32_e32 v68, 0x88, v238
	s_nop 0
	v_cndmask_b32_e32 v115, v226, v115, vcc
	v_cmp_le_u32_e32 vcc, v68, v235
	v_add_u32_e32 v68, 0xa8, v238
	s_nop 0
	v_cndmask_b32_e32 v100, v226, v100, vcc
	v_cmp_le_u32_e32 vcc, v68, v235
	v_add_u32_e32 v68, 0x89, v238
	s_nop 0
	v_cndmask_b32_e32 v116, v226, v116, vcc
	v_cmp_le_u32_e32 vcc, v68, v235
	v_add_u32_e32 v68, 0xa9, v238
	s_nop 0
	v_cndmask_b32_e32 v101, v226, v101, vcc
	v_cmp_le_u32_e32 vcc, v68, v235
	v_add_u32_e32 v68, 0x8a, v238
	s_nop 0
	v_cndmask_b32_e32 v117, v226, v117, vcc
	v_cmp_le_u32_e32 vcc, v68, v235
	v_add_u32_e32 v68, 0xaa, v238
	s_nop 0
	v_cndmask_b32_e32 v102, v226, v102, vcc
	v_cmp_le_u32_e32 vcc, v68, v235
	v_add_u32_e32 v68, 0x8b, v238
	s_nop 0
	v_cndmask_b32_e32 v118, v226, v118, vcc
	v_cmp_le_u32_e32 vcc, v68, v235
	v_add_u32_e32 v68, 0xab, v238
	s_nop 0
	v_cndmask_b32_e32 v103, v226, v103, vcc
	v_cmp_le_u32_e32 vcc, v68, v235
	v_add_u32_e32 v68, 0x90, v238
	s_nop 0
	v_cndmask_b32_e32 v119, v226, v119, vcc
	v_cmp_le_u32_e32 vcc, v68, v235
	v_add_u32_e32 v68, 0xb0, v238
	s_nop 0
	v_cndmask_b32_e32 v104, v226, v104, vcc
	v_cmp_le_u32_e32 vcc, v68, v235
	v_add_u32_e32 v68, 0x91, v238
	s_nop 0
	v_cndmask_b32_e32 v120, v226, v120, vcc
	v_cmp_le_u32_e32 vcc, v68, v235
	v_add_u32_e32 v68, 0xb1, v238
	s_nop 0
	v_cndmask_b32_e32 v105, v226, v105, vcc
	v_cmp_le_u32_e32 vcc, v68, v235
	v_add_u32_e32 v68, 0x92, v238
	s_nop 0
	v_cndmask_b32_e32 v121, v226, v121, vcc
	v_cmp_le_u32_e32 vcc, v68, v235
	v_add_u32_e32 v68, 0xb2, v238
	s_nop 0
	v_cndmask_b32_e32 v106, v226, v106, vcc
	v_cmp_le_u32_e32 vcc, v68, v235
	v_add_u32_e32 v68, 0x93, v238
	s_nop 0
	v_cndmask_b32_e32 v122, v226, v122, vcc
	v_cmp_le_u32_e32 vcc, v68, v235
	v_add_u32_e32 v68, 0xb3, v238
	s_nop 0
	v_cndmask_b32_e32 v107, v226, v107, vcc
	v_cmp_le_u32_e32 vcc, v68, v235
	v_add_u32_e32 v68, 0x98, v238
	s_nop 0
	v_cndmask_b32_e32 v123, v226, v123, vcc
	v_cmp_le_u32_e32 vcc, v68, v235
	v_add_u32_e32 v68, 0xb8, v238
	s_nop 0
	v_cndmask_b32_e32 v108, v226, v108, vcc
	v_cmp_le_u32_e32 vcc, v68, v235
	v_add_u32_e32 v68, 0x99, v238
	s_nop 0
	v_cndmask_b32_e32 v124, v226, v124, vcc
	v_cmp_le_u32_e32 vcc, v68, v235
	v_add_u32_e32 v68, 0xb9, v238
	s_nop 0
	v_cndmask_b32_e32 v109, v226, v109, vcc
	v_cmp_le_u32_e32 vcc, v68, v235
	v_add_u32_e32 v68, 0x9a, v238
	s_nop 0
	v_cndmask_b32_e32 v125, v226, v125, vcc
	v_cmp_le_u32_e32 vcc, v68, v235
	v_add_u32_e32 v68, 0xba, v238
	s_nop 0
	v_cndmask_b32_e32 v110, v226, v110, vcc
	v_cmp_le_u32_e32 vcc, v68, v235
	v_add_u32_e32 v68, 0x9b, v238
	s_nop 0
	v_cndmask_b32_e32 v126, v226, v126, vcc
	v_cmp_le_u32_e32 vcc, v68, v235
	v_add_u32_e32 v68, 0xbb, v238
	s_nop 0
	v_cndmask_b32_e32 v111, v226, v111, vcc
	v_cmp_le_u32_e32 vcc, v68, v235
	s_nop 1
	v_cndmask_b32_e32 v127, v226, v127, vcc
	s_branch .LBB0_870
